# residual epilogue: per-block counted waits in the first group (stores start after block 0 lands)
# baseline (speedup 1.0000x reference)
; __device__ __forceinline__ unsigned cvt_pk_bf16(float lo, float hi) { unsigned r; asm volatile("v_cvt_pk_bf16_f32 %0, %1, %2" : "=v"(r) : "v"(lo), "v"(hi)); return r; }
;     __device__ __forceinline__ void operator()(const f32x4 (&acc)[2][2][4][2], const Unit& u, int wr, int wc, int fr, int fq) const {
;     ...
;         for (int bj = 0; bj < 2; ++bj) {
;             const int c = col0 + bj * HALF;
;             const f32x4 g0 = *(const f32x4*)(gate + c), g1 = *(const f32x4*)(gate + c + 4), n0 = *(const f32x4*)(gn + c), n1 = *(const f32x4*)(gn + c + 4);
;             const f32x4 b0 = bias ? *(const f32x4*)(bias + c) : (f32x4){0.f, 0.f, 0.f, 0.f}, b1 = bias ? *(const f32x4*)(bias + c + 4) : (f32x4){0.f, 0.f, 0.f, 0.f};
; #pragma unroll
;             for (int ai = 0; ai < 2; ++ai) {
;                 f32x4 xa[4][2];
; #pragma unroll
;                 for (int m = 0; m < 4; ++m) { const unsigned off = (unsigned)(row0 + ai * HALF + m * 16) * 1024u + (unsigned)c; xa[m][0] = *(const f32x4*)(xold + off); xa[m][1] = *(const f32x4*)(xold + off + 4); }
; #pragma unroll
;                 for (int m = 0; m < 4; ++m) {
;                     const unsigned off = (unsigned)(row0 + ai * HALF + m * 16) * 1024u + (unsigned)c;
;                     const f32x4 x0 = xa[m][0], x1 = xa[m][1];
;                     const f32x4 y0 = x0 + g0 * (acc[ai][bj][m][0] + b0), y1 = x1 + g1 * (acc[ai][bj][m][1] + b1);
;                     if (!dry) { *(f32x4*)(xnew + off) = y0; *(f32x4*)(xnew + off + 4) = y1; }
;                     ss[ai][m] += (y0[0] * y0[0] + y0[1] * y0[1]) + (y0[2] * y0[2] + y0[3] * y0[3]) + (y1[0] * y1[0] + y1[1] * y1[1]) + (y1[2] * y1[2] + y1[3] * y1[3]);
;                     asm volatile("" : "+v"(ss[ai][m]));
;                     const f32x4 z0 = y0 * n0, z1 = y1 * n1;
;                     u32x4 w; w.x = cvt_pk_bf16(z0[0], z0[1]); w.y = cvt_pk_bf16(z0[2], z0[3]); w.z = cvt_pk_bf16(z1[0], z1[1]); w.w = cvt_pk_bf16(z1[2], z1[3]);
;                     if (!dry && xb) *(u32x4*)(xb + off) = w;
.Lre_nobias:
	s_cmp_lg_u64 s[76:77], 0
	s_cselect_b64 vcc, -1, 0
	s_add_u32 s44, s66, 0x0
	s_addc_u32 s45, s67, 0
	global_load_dwordx4 v[144:147], v180, s[44:45]
	global_load_dwordx4 v[148:151], v181, s[44:45]
	s_add_u32 s44, s66, 0x10000
	s_addc_u32 s45, s67, 0
	global_load_dwordx4 v[152:155], v180, s[44:45]
	global_load_dwordx4 v[156:159], v181, s[44:45]
	s_add_u32 s44, s66, 0x20000
	s_addc_u32 s45, s67, 0
	global_load_dwordx4 v[160:163], v180, s[44:45]
	global_load_dwordx4 v[164:167], v181, s[44:45]
	s_add_u32 s44, s66, 0x30000
	s_addc_u32 s45, s67, 0
	global_load_dwordx4 v[168:171], v180, s[44:45]
	global_load_dwordx4 v[172:175], v181, s[44:45]
	s_add_u32 s44, s66, 0x80000
	s_addc_u32 s45, s67, 0
	global_load_dwordx4 v[176:179], v180, s[44:45]
	global_load_dwordx4 v[196:199], v181, s[44:45]
	s_add_u32 s44, s66, 0x90000
	s_addc_u32 s45, s67, 0
	global_load_dwordx4 v[200:203], v180, s[44:45]
	global_load_dwordx4 v[204:207], v181, s[44:45]
	s_add_u32 s44, s66, 0xa0000
	s_addc_u32 s45, s67, 0
	global_load_dwordx4 v[208:211], v180, s[44:45]
	global_load_dwordx4 v[232:235], v181, s[44:45]
	s_add_u32 s44, s66, 0xb0000
	s_addc_u32 s45, s67, 0
	global_load_dwordx4 v[236:239], v180, s[44:45]
	global_load_dwordx4 v[240:243], v181, s[44:45]
	ds_write_b128 v130, v[126:129]
	ds_write_b128 v130, v[122:125] offset:16
	ds_read_b128 v[126:129], v131
	ds_read_b128 v[122:125], v131 offset:1152
	ds_write_b128 v130, v[110:113]
	ds_write_b128 v130, v[102:105] offset:16
	ds_read_b128 v[110:113], v131
	ds_read_b128 v[102:105], v131 offset:1152
	ds_write_b128 v130, v[94:97]
	ds_write_b128 v130, v[86:89] offset:16
	ds_read_b128 v[94:97], v131
	ds_read_b128 v[86:89], v131 offset:1152
	ds_write_b128 v130, v[78:81]
	ds_write_b128 v130, v[70:73] offset:16
	ds_read_b128 v[78:81], v131
	ds_read_b128 v[70:73], v131 offset:1152
	s_waitcnt vmcnt(14) lgkmcnt(0)
	v_pk_add_f32 v[126:127], v[126:127], v[136:137]
	v_pk_add_f32 v[128:129], v[128:129], v[138:139]
	v_pk_add_f32 v[122:123], v[122:123], v[136:137]
	v_pk_add_f32 v[124:125], v[124:125], v[138:139]
	s_add_u32 s44, s60, 0x0
	s_addc_u32 s45, s61, 0
	v_pk_fma_f32 v[144:145], v[132:133], v[126:127], v[144:145]
	v_pk_fma_f32 v[146:147], v[134:135], v[128:129], v[146:147]
	v_pk_fma_f32 v[148:149], v[132:133], v[122:123], v[148:149]
	v_pk_fma_f32 v[150:151], v[134:135], v[124:125], v[150:151]
	global_store_dwordx4 v180, v[144:147], s[44:45]
	global_store_dwordx4 v181, v[148:151], s[44:45]
	v_pk_mul_f32 v[126:127], v[140:141], v[144:145]
	v_pk_mul_f32 v[128:129], v[142:143], v[146:147]
	v_pk_mul_f32 v[122:123], v[140:141], v[148:149]
	v_pk_mul_f32 v[124:125], v[142:143], v[150:151]
	v_mul_f32_e32 v231, v145, v145
	v_mul_f32_e32 v244, v147, v147
	v_fmac_f32_e32 v231, v144, v144
	v_fmac_f32_e32 v244, v146, v146
	v_cvt_pk_bf16_f32 v126, v126, v127
	v_cvt_pk_bf16_f32 v127, v128, v129
	v_add_f32_e32 v128, v231, v244
	v_cvt_pk_bf16_f32 v122, v122, v123
	v_cvt_pk_bf16_f32 v123, v124, v125
	v_mul_f32_e32 v231, v149, v149
	v_mul_f32_e32 v244, v151, v151
	v_fmac_f32_e32 v231, v148, v148
	v_fmac_f32_e32 v244, v150, v150
	s_add_u32 s100, s64, 0x0
	s_addc_u32 s101, s65, 0
	v_add_f32_e32 v124, v231, v244
	s_cbranch_vccz .Lre_nx0_0
	global_store_dwordx2 v194, v[126:127], s[100:101]
	global_store_dwordx2 v195, v[122:123], s[100:101]
; __device__ __forceinline__ unsigned cvt_pk_bf16(float lo, float hi) { unsigned r; asm volatile("v_cvt_pk_bf16_f32 %0, %1, %2" : "=v"(r) : "v"(lo), "v"(hi)); return r; }
;     __device__ __forceinline__ void operator()(const f32x4 (&acc)[2][2][4][2], const Unit& u, int wr, int wc, int fr, int fq) const {
;     ...
;                 for (int m = 0; m < 4; ++m) {
;                     const unsigned off = (unsigned)(row0 + ai * HALF + m * 16) * 1024u + (unsigned)c;
;                     const f32x4 x0 = xa[m][0], x1 = xa[m][1];
;                     const f32x4 y0 = x0 + g0 * (acc[ai][bj][m][0] + b0), y1 = x1 + g1 * (acc[ai][bj][m][1] + b1);
;                     if (!dry) { *(f32x4*)(xnew + off) = y0; *(f32x4*)(xnew + off + 4) = y1; }
;                     ss[ai][m] += (y0[0] * y0[0] + y0[1] * y0[1]) + (y0[2] * y0[2] + y0[3] * y0[3]) + (y1[0] * y1[0] + y1[1] * y1[1]) + (y1[2] * y1[2] + y1[3] * y1[3]);
;                     asm volatile("" : "+v"(ss[ai][m]));
;                     const f32x4 z0 = y0 * n0, z1 = y1 * n1;
;                     u32x4 w; w.x = cvt_pk_bf16(z0[0], z0[1]); w.y = cvt_pk_bf16(z0[2], z0[3]); w.z = cvt_pk_bf16(z1[0], z1[1]); w.w = cvt_pk_bf16(z1[2], z1[3]);
;                     if (!dry && xb) *(u32x4*)(xb + off) = w;
.Lre_nx0_0:
	s_waitcnt vmcnt(14)
	v_pk_add_f32 v[110:111], v[110:111], v[136:137]
	v_pk_add_f32 v[112:113], v[112:113], v[138:139]
	v_pk_add_f32 v[102:103], v[102:103], v[136:137]
	v_pk_add_f32 v[104:105], v[104:105], v[138:139]
	s_add_u32 s44, s60, 0x10000
	s_addc_u32 s45, s61, 0
	v_pk_fma_f32 v[152:153], v[132:133], v[110:111], v[152:153]
	v_pk_fma_f32 v[154:155], v[134:135], v[112:113], v[154:155]
	v_pk_fma_f32 v[156:157], v[132:133], v[102:103], v[156:157]
	v_pk_fma_f32 v[158:159], v[134:135], v[104:105], v[158:159]
	global_store_dwordx4 v180, v[152:155], s[44:45]
	global_store_dwordx4 v181, v[156:159], s[44:45]
	v_pk_mul_f32 v[110:111], v[140:141], v[152:153]
	v_pk_mul_f32 v[112:113], v[142:143], v[154:155]
	v_pk_mul_f32 v[102:103], v[140:141], v[156:157]
	v_pk_mul_f32 v[104:105], v[142:143], v[158:159]
	v_mul_f32_e32 v231, v153, v153
	v_mul_f32_e32 v244, v155, v155
	v_fmac_f32_e32 v231, v152, v152
	v_fmac_f32_e32 v244, v154, v154
	v_cvt_pk_bf16_f32 v110, v110, v111
	v_cvt_pk_bf16_f32 v111, v112, v113
	v_add_f32_e32 v112, v231, v244
	v_cvt_pk_bf16_f32 v102, v102, v103
	v_cvt_pk_bf16_f32 v103, v104, v105
	v_mul_f32_e32 v231, v157, v157
	v_mul_f32_e32 v244, v159, v159
	v_fmac_f32_e32 v231, v156, v156
	v_fmac_f32_e32 v244, v158, v158
	s_add_u32 s100, s64, 0x8000
	s_addc_u32 s101, s65, 0
	v_add_f32_e32 v104, v231, v244
	s_cbranch_vccz .Lre_nx0_1
	global_store_dwordx2 v194, v[110:111], s[100:101]
	global_store_dwordx2 v195, v[102:103], s[100:101]
.Lre_nx0_1:
	s_waitcnt vmcnt(14)
	v_pk_add_f32 v[94:95], v[94:95], v[136:137]
	v_pk_add_f32 v[96:97], v[96:97], v[138:139]
	v_pk_add_f32 v[86:87], v[86:87], v[136:137]
	v_pk_add_f32 v[88:89], v[88:89], v[138:139]
	s_add_u32 s44, s60, 0x20000
	s_addc_u32 s45, s61, 0
	v_pk_fma_f32 v[160:161], v[132:133], v[94:95], v[160:161]
	v_pk_fma_f32 v[162:163], v[134:135], v[96:97], v[162:163]
	v_pk_fma_f32 v[164:165], v[132:133], v[86:87], v[164:165]
	v_pk_fma_f32 v[166:167], v[134:135], v[88:89], v[166:167]
	global_store_dwordx4 v180, v[160:163], s[44:45]
	global_store_dwordx4 v181, v[164:167], s[44:45]
	v_pk_mul_f32 v[94:95], v[140:141], v[160:161]
	v_pk_mul_f32 v[96:97], v[142:143], v[162:163]
	v_pk_mul_f32 v[86:87], v[140:141], v[164:165]
	v_pk_mul_f32 v[88:89], v[142:143], v[166:167]
	v_mul_f32_e32 v231, v161, v161
	v_mul_f32_e32 v244, v163, v163
	v_fmac_f32_e32 v231, v160, v160
	v_fmac_f32_e32 v244, v162, v162
	v_cvt_pk_bf16_f32 v94, v94, v95
	v_cvt_pk_bf16_f32 v95, v96, v97
	v_add_f32_e32 v96, v231, v244
	v_cvt_pk_bf16_f32 v86, v86, v87
	v_cvt_pk_bf16_f32 v87, v88, v89
	v_mul_f32_e32 v231, v165, v165
	v_mul_f32_e32 v244, v167, v167
	v_fmac_f32_e32 v231, v164, v164
	v_fmac_f32_e32 v244, v166, v166
	s_add_u32 s100, s64, 0x10000
	s_addc_u32 s101, s65, 0
	v_add_f32_e32 v88, v231, v244
	s_cbranch_vccz .Lre_nx0_2
	global_store_dwordx2 v194, v[94:95], s[100:101]
	global_store_dwordx2 v195, v[86:87], s[100:101]
.Lre_nx0_2:
	s_waitcnt vmcnt(14)
	v_pk_add_f32 v[78:79], v[78:79], v[136:137]
	v_pk_add_f32 v[80:81], v[80:81], v[138:139]
	v_pk_add_f32 v[70:71], v[70:71], v[136:137]
	v_pk_add_f32 v[72:73], v[72:73], v[138:139]
	s_add_u32 s44, s60, 0x30000
	s_addc_u32 s45, s61, 0
	v_pk_fma_f32 v[168:169], v[132:133], v[78:79], v[168:169]
	v_pk_fma_f32 v[170:171], v[134:135], v[80:81], v[170:171]
	v_pk_fma_f32 v[172:173], v[132:133], v[70:71], v[172:173]
	v_pk_fma_f32 v[174:175], v[134:135], v[72:73], v[174:175]
	global_store_dwordx4 v180, v[168:171], s[44:45]
	global_store_dwordx4 v181, v[172:175], s[44:45]
	v_pk_mul_f32 v[78:79], v[140:141], v[168:169]
	v_pk_mul_f32 v[80:81], v[142:143], v[170:171]
	v_pk_mul_f32 v[70:71], v[140:141], v[172:173]
	v_pk_mul_f32 v[72:73], v[142:143], v[174:175]
	v_mul_f32_e32 v231, v169, v169
	v_mul_f32_e32 v244, v171, v171
	v_fmac_f32_e32 v231, v168, v168
	v_fmac_f32_e32 v244, v170, v170
	v_cvt_pk_bf16_f32 v78, v78, v79
	v_cvt_pk_bf16_f32 v79, v80, v81
	v_add_f32_e32 v80, v231, v244
	v_cvt_pk_bf16_f32 v70, v70, v71
	v_cvt_pk_bf16_f32 v71, v72, v73
	v_mul_f32_e32 v231, v173, v173
	v_mul_f32_e32 v244, v175, v175
	v_fmac_f32_e32 v231, v172, v172
	v_fmac_f32_e32 v244, v174, v174
	s_add_u32 s100, s64, 0x18000
	s_addc_u32 s101, s65, 0
	v_add_f32_e32 v72, v231, v244
	s_cbranch_vccz .Lre_nx0_3
	global_store_dwordx2 v194, v[78:79], s[100:101]
	global_store_dwordx2 v195, v[70:71], s[100:101]
